# rwkv prep part 1 (token-shifted LoRA inputs) rewritten branch-free with all 27 loads in flight before one wait
# speedup vs baseline: 1.0133x; 1.0045x over previous
; __device__ __forceinline__ void rwkv_prep_unit(const Args& c, int u, int l, LAS unsigned char* lds) {
;     ...
;     for (int it = 0; it < 9; ++it) {
;         const int idx = tid + it * NTHR;
;         const int t = idx / 288, j = idx % 288, tok = tok0 + t;
;         const bool use = (j < 256) || (l > 0);
;         const int col = (j < 256) ? 1536 + j : 1792 + (j - 256);
;         const float m_ = (j < 256) ? mu[1536 + j] : ((l > 0) ? c.in[5 + z_][(size_t)(l - 1) * 32 + (j - 256)] : 0.f);
;         const bool hp = (tok & (T - 1)) != 0;
;         const float cur = bf2f(P[(size_t)tok * PW + col]);
;         const float pv = bf2f(P[(size_t)(hp ? tok - 1 : tok) * PW + col]);
;         const float prev = hp ? pv : 0.f;
.LBB0_308:
	v_readlane_b32 s0, v252, 57
	v_readlane_b32 s2, v252, 59
	v_readlane_b32 s3, v252, 60
	v_mov_b32_e32 v116, v179
	v_readlane_b32 s1, v252, 58
	s_mov_b64 s[24:25], s[2:3]
	s_mov_b32 s0, s15
	s_ashr_i32 s1, s0, 31
	s_lshl_b64 s[0:1], s[0:1], 3
	v_readlane_b32 s2, v251, 0
	v_readlane_b32 s3, v251, 1
	s_add_u32 s12, s2, s0
	s_addc_u32 s13, s3, s1
	s_load_dwordx2 s[0:1], s[12:13], 0x20
	v_readlane_b32 s2, v250, 45
	v_readfirstlane_b32 s16, v116
	s_waitcnt vmcnt(0) lgkmcnt(0)
	s_barrier
	s_add_u32 s40, s0, s2
	v_readlane_b32 s0, v250, 44
	s_addc_u32 s41, s1, s0
	v_readlane_b32 s0, v250, 46
	v_readlane_b32 s1, v250, 47
	v_readlane_b32 s2, v250, 48
	v_readlane_b32 s3, v250, 49
	s_load_dwordx2 s[6:7], s[12:13], 0x28
	s_add_u32 s30, s24, 0xa800000
	s_addc_u32 s31, s25, 0
	s_add_u32 s4, s40, 0x1800
	s_addc_u32 s5, s41, 0
	s_mov_b32 s9, 0x38e38e39
	v_cndmask_b32_e64 v0, 0, 1, s[0:1]
	v_mov_b32_e32 v65, 0
	v_mov_b32_e32 v71, 0x3800
	v_cmp_ne_u32_e64 s[42:43], 1, v0
	s_waitcnt lgkmcnt(0)
	s_add_u32 s6, s6, s2
	s_addc_u32 s7, s7, s3
	s_add_u32 s6, s6, 0xfffffc00
	s_addc_u32 s7, s7, -1
	v_mul_hi_i32 v66, v116, s9
	v_lshrrev_b32_e32 v67, 31, v66
	v_ashrrev_i32_e32 v66, 6, v66
	v_add_u32_e32 v21, v66, v67
	v_mul_i32_i24_e32 v66, 0x120, v21
	v_sub_u32_e32 v12, v116, v66
	v_mov_b32_e32 v64, v12
	v_cmp_lt_i32_e32 vcc, 0xff, v12
	v_lshl_add_u64 v[76:77], v[64:65], 2, s[4:5]
	v_lshl_add_u64 v[78:79], v[64:65], 2, s[6:7]
	s_and_b64 vcc, vcc, s[0:1]
	v_add3_u32 v66, s14, v21, -3
	v_cndmask_b32_e32 v76, v76, v78, vcc
	v_cndmask_b32_e32 v77, v77, v79, vcc
	v_and_b32_e32 v67, 0x7ff, v66
	global_load_dword v30, v[76:77], off
	v_cmp_ne_u32_e32 vcc, 0, v67
	v_mul_u32_u24_e32 v69, 0x3800, v66
	v_lshl_add_u32 v69, v12, 1, v69
	v_cndmask_b32_e32 v70, 0, v71, vcc
	v_sub_u32_e32 v70, v69, v70
	global_load_ushort v39, v69, s[30:31] offset:3072
	global_load_ushort v52, v70, s[30:31] offset:3072
	v_add_u32_e32 v63, 0x200, v116
	v_mul_hi_i32 v66, v63, s9
	v_lshrrev_b32_e32 v67, 31, v66
	v_ashrrev_i32_e32 v66, 6, v66
	v_add_u32_e32 v22, v66, v67
	v_mul_i32_i24_e32 v66, 0x120, v22
	v_sub_u32_e32 v13, v63, v66
	v_mov_b32_e32 v64, v13
	v_cmp_lt_i32_e32 vcc, 0xff, v13
	v_lshl_add_u64 v[76:77], v[64:65], 2, s[4:5]
	v_lshl_add_u64 v[78:79], v[64:65], 2, s[6:7]
	s_and_b64 vcc, vcc, s[0:1]
	v_add3_u32 v66, s14, v22, -3
	v_cndmask_b32_e32 v76, v76, v78, vcc
	v_cndmask_b32_e32 v77, v77, v79, vcc
	v_and_b32_e32 v67, 0x7ff, v66
	global_load_dword v31, v[76:77], off
	v_cmp_ne_u32_e32 vcc, 0, v67
	v_mul_u32_u24_e32 v69, 0x3800, v66
	v_lshl_add_u32 v69, v13, 1, v69
	v_cndmask_b32_e32 v70, 0, v71, vcc
	v_sub_u32_e32 v70, v69, v70
	global_load_ushort v40, v69, s[30:31] offset:3072
	global_load_ushort v53, v70, s[30:31] offset:3072
	v_add_u32_e32 v63, 0x400, v116
	v_mul_hi_i32 v66, v63, s9
	v_lshrrev_b32_e32 v67, 31, v66
	v_ashrrev_i32_e32 v66, 6, v66
	v_add_u32_e32 v23, v66, v67
	v_mul_i32_i24_e32 v66, 0x120, v23
	v_sub_u32_e32 v14, v63, v66
	v_mov_b32_e32 v64, v14
	v_cmp_lt_i32_e32 vcc, 0xff, v14
	v_lshl_add_u64 v[76:77], v[64:65], 2, s[4:5]
	v_lshl_add_u64 v[78:79], v[64:65], 2, s[6:7]
	s_and_b64 vcc, vcc, s[0:1]
	v_add3_u32 v66, s14, v23, -3
	v_cndmask_b32_e32 v76, v76, v78, vcc
	v_cndmask_b32_e32 v77, v77, v79, vcc
	v_and_b32_e32 v67, 0x7ff, v66
	global_load_dword v32, v[76:77], off
	v_cmp_ne_u32_e32 vcc, 0, v67
	v_mul_u32_u24_e32 v69, 0x3800, v66
	v_lshl_add_u32 v69, v14, 1, v69
	v_cndmask_b32_e32 v70, 0, v71, vcc
	v_sub_u32_e32 v70, v69, v70
	global_load_ushort v41, v69, s[30:31] offset:3072
	global_load_ushort v54, v70, s[30:31] offset:3072
	v_add_u32_e32 v63, 0x600, v116
	v_mul_hi_i32 v66, v63, s9
	v_lshrrev_b32_e32 v67, 31, v66
	v_ashrrev_i32_e32 v66, 6, v66
	v_add_u32_e32 v24, v66, v67
	v_mul_i32_i24_e32 v66, 0x120, v24
	v_sub_u32_e32 v15, v63, v66
	v_mov_b32_e32 v64, v15
	v_cmp_lt_i32_e32 vcc, 0xff, v15
	v_lshl_add_u64 v[76:77], v[64:65], 2, s[4:5]
	v_lshl_add_u64 v[78:79], v[64:65], 2, s[6:7]
	s_and_b64 vcc, vcc, s[0:1]
	v_add3_u32 v66, s14, v24, -3
	v_cndmask_b32_e32 v76, v76, v78, vcc
	v_cndmask_b32_e32 v77, v77, v79, vcc
	v_and_b32_e32 v67, 0x7ff, v66
	global_load_dword v33, v[76:77], off
	v_cmp_ne_u32_e32 vcc, 0, v67
	v_mul_u32_u24_e32 v69, 0x3800, v66
	v_lshl_add_u32 v69, v15, 1, v69
	v_cndmask_b32_e32 v70, 0, v71, vcc
	v_sub_u32_e32 v70, v69, v70
	global_load_ushort v42, v69, s[30:31] offset:3072
	global_load_ushort v55, v70, s[30:31] offset:3072
	v_add_u32_e32 v63, 0x800, v116
	v_mul_hi_i32 v66, v63, s9
	v_lshrrev_b32_e32 v67, 31, v66
	v_ashrrev_i32_e32 v66, 6, v66
	v_add_u32_e32 v25, v66, v67
	v_mul_i32_i24_e32 v66, 0x120, v25
	v_sub_u32_e32 v16, v63, v66
	v_mov_b32_e32 v64, v16
	v_cmp_lt_i32_e32 vcc, 0xff, v16
	v_lshl_add_u64 v[76:77], v[64:65], 2, s[4:5]
	v_lshl_add_u64 v[78:79], v[64:65], 2, s[6:7]
	s_and_b64 vcc, vcc, s[0:1]
	v_add3_u32 v66, s14, v25, -3
	v_cndmask_b32_e32 v76, v76, v78, vcc
	v_cndmask_b32_e32 v77, v77, v79, vcc
	v_and_b32_e32 v67, 0x7ff, v66
	global_load_dword v34, v[76:77], off
	v_cmp_ne_u32_e32 vcc, 0, v67
	v_mul_u32_u24_e32 v69, 0x3800, v66
	v_lshl_add_u32 v69, v16, 1, v69
	v_cndmask_b32_e32 v70, 0, v71, vcc
	v_sub_u32_e32 v70, v69, v70
	global_load_ushort v43, v69, s[30:31] offset:3072
	global_load_ushort v58, v70, s[30:31] offset:3072
	v_add_u32_e32 v63, 0xa00, v116
	v_mul_hi_i32 v66, v63, s9
	v_lshrrev_b32_e32 v67, 31, v66
	v_ashrrev_i32_e32 v66, 6, v66
	v_add_u32_e32 v26, v66, v67
	v_mul_i32_i24_e32 v66, 0x120, v26
	v_sub_u32_e32 v17, v63, v66
	v_mov_b32_e32 v64, v17
	v_cmp_lt_i32_e32 vcc, 0xff, v17
	v_lshl_add_u64 v[76:77], v[64:65], 2, s[4:5]
	v_lshl_add_u64 v[78:79], v[64:65], 2, s[6:7]
	s_and_b64 vcc, vcc, s[0:1]
; __device__ __forceinline__ unsigned f2bf(float f) { return pk2(f, f) & 0xffffu; }
; __device__ __forceinline__ float sigmoidf_(float x) { return __builtin_amdgcn_rcpf(1.0f + __expf(-x)); }
; __device__ __forceinline__ float tanhf_(float x) { const float e = __expf(-2.0f * fabsf(x)); const float t = (1.0f - e) * __builtin_amdgcn_rcpf(1.0f + e); return x < 0.f ? -t : t; }
; __device__ __forceinline__ void rwkv_prep_unit(const Args& c, int u, int l, LAS unsigned char* lds) {
;     ...
;         const int t = idx / 288, j = idx % 288, tok = tok0 + t;
;         const bool use = (j < 256) || (l > 0);
;         const int col = (j < 256) ? 1536 + j : 1792 + (j - 256);
;         const float m_ = (j < 256) ? mu[1536 + j] : ((l > 0) ? c.in[5 + z_][(size_t)(l - 1) * 32 + (j - 256)] : 0.f);
;         const bool hp = (tok & (T - 1)) != 0;
;         const float cur = bf2f(P[(size_t)tok * PW + col]);
;         const float pv = bf2f(P[(size_t)(hp ? tok - 1 : tok) * PW + col]);
;         const float prev = hp ? pv : 0.f;
;         float x = cur + (prev - cur) * m_;
;         const float xt = tanhf_(x), xs_ = sigmoidf_(x);
;         x = (j < 64) ? xt : ((j >= 128 && j < 256) ? xs_ : x);
;         xs[t * 296 + j] = (bf16)f2bf(use ? x : 0.f);
	v_add3_u32 v66, s14, v26, -3
	v_cndmask_b32_e32 v76, v76, v78, vcc
	v_cndmask_b32_e32 v77, v77, v79, vcc
	v_and_b32_e32 v67, 0x7ff, v66
	global_load_dword v35, v[76:77], off
	v_cmp_ne_u32_e32 vcc, 0, v67
	v_mul_u32_u24_e32 v69, 0x3800, v66
	v_lshl_add_u32 v69, v17, 1, v69
	v_cndmask_b32_e32 v70, 0, v71, vcc
	v_sub_u32_e32 v70, v69, v70
	global_load_ushort v44, v69, s[30:31] offset:3072
	global_load_ushort v59, v70, s[30:31] offset:3072
	v_add_u32_e32 v63, 0xc00, v116
	v_mul_hi_i32 v66, v63, s9
	v_lshrrev_b32_e32 v67, 31, v66
	v_ashrrev_i32_e32 v66, 6, v66
	v_add_u32_e32 v27, v66, v67
	v_mul_i32_i24_e32 v66, 0x120, v27
	v_sub_u32_e32 v18, v63, v66
	v_mov_b32_e32 v64, v18
	v_cmp_lt_i32_e32 vcc, 0xff, v18
	v_lshl_add_u64 v[76:77], v[64:65], 2, s[4:5]
	v_lshl_add_u64 v[78:79], v[64:65], 2, s[6:7]
	s_and_b64 vcc, vcc, s[0:1]
	v_add3_u32 v66, s14, v27, -3
	v_cndmask_b32_e32 v76, v76, v78, vcc
	v_cndmask_b32_e32 v77, v77, v79, vcc
	v_and_b32_e32 v67, 0x7ff, v66
	global_load_dword v36, v[76:77], off
	v_cmp_ne_u32_e32 vcc, 0, v67
	v_mul_u32_u24_e32 v69, 0x3800, v66
	v_lshl_add_u32 v69, v18, 1, v69
	v_cndmask_b32_e32 v70, 0, v71, vcc
	v_sub_u32_e32 v70, v69, v70
	global_load_ushort v45, v69, s[30:31] offset:3072
	global_load_ushort v60, v70, s[30:31] offset:3072
	v_add_u32_e32 v63, 0xe00, v116
	v_mul_hi_i32 v66, v63, s9
	v_lshrrev_b32_e32 v67, 31, v66
	v_ashrrev_i32_e32 v66, 6, v66
	v_add_u32_e32 v28, v66, v67
	v_mul_i32_i24_e32 v66, 0x120, v28
	v_sub_u32_e32 v19, v63, v66
	v_mov_b32_e32 v64, v19
	v_cmp_lt_i32_e32 vcc, 0xff, v19
	v_lshl_add_u64 v[76:77], v[64:65], 2, s[4:5]
	v_lshl_add_u64 v[78:79], v[64:65], 2, s[6:7]
	s_and_b64 vcc, vcc, s[0:1]
	v_add3_u32 v66, s14, v28, -3
	v_cndmask_b32_e32 v76, v76, v78, vcc
	v_cndmask_b32_e32 v77, v77, v79, vcc
	v_and_b32_e32 v67, 0x7ff, v66
	global_load_dword v37, v[76:77], off
	v_cmp_ne_u32_e32 vcc, 0, v67
	v_mul_u32_u24_e32 v69, 0x3800, v66
	v_lshl_add_u32 v69, v19, 1, v69
	v_cndmask_b32_e32 v70, 0, v71, vcc
	v_sub_u32_e32 v70, v69, v70
	global_load_ushort v46, v69, s[30:31] offset:3072
	global_load_ushort v61, v70, s[30:31] offset:3072
	v_add_u32_e32 v63, 0x1000, v116
	v_mul_hi_i32 v66, v63, s9
	v_lshrrev_b32_e32 v67, 31, v66
	v_ashrrev_i32_e32 v66, 6, v66
	v_add_u32_e32 v29, v66, v67
	v_mul_i32_i24_e32 v66, 0x120, v29
	v_sub_u32_e32 v20, v63, v66
	v_mov_b32_e32 v64, v20
	v_cmp_lt_i32_e32 vcc, 0xff, v20
	v_lshl_add_u64 v[76:77], v[64:65], 2, s[4:5]
	v_lshl_add_u64 v[78:79], v[64:65], 2, s[6:7]
	s_and_b64 vcc, vcc, s[0:1]
	v_add3_u32 v66, s14, v29, -3
	v_cndmask_b32_e32 v76, v76, v78, vcc
	v_cndmask_b32_e32 v77, v77, v79, vcc
	v_and_b32_e32 v67, 0x7ff, v66
	global_load_dword v38, v[76:77], off
	v_cmp_ne_u32_e32 vcc, 0, v67
	v_mul_u32_u24_e32 v69, 0x3800, v66
	v_lshl_add_u32 v69, v20, 1, v69
	v_cndmask_b32_e32 v70, 0, v71, vcc
	v_sub_u32_e32 v70, v69, v70
	global_load_ushort v47, v69, s[30:31] offset:3072
	global_load_ushort v62, v70, s[30:31] offset:3072
	s_movk_i32 s8, 0x100
	s_movk_i32 s9, 0x80
	s_waitcnt vmcnt(0)
	v_add3_u32 v66, s14, v21, -3
	v_and_b32_e32 v67, 0x7ff, v66
	v_cmp_ne_u32_e64 s[2:3], 0, v67
	v_lshlrev_b32_e32 v39, 16, v39
	v_lshlrev_b32_e32 v52, 16, v52
	v_cmp_gt_i32_e64 s[44:45], s8, v12
	v_cndmask_b32_e64 v52, 0, v52, s[2:3]
	v_sub_f32_e32 v52, v52, v39
	v_fmac_f32_e32 v39, v30, v52
	v_mul_f32_e64 v72, |v39|, -2.0
	v_mul_f32_e32 v72, 0x3fb8aa3b, v72
	v_exp_f32_e32 v72, v72
	v_cmp_gt_f32_e64 s[2:3], 0, v39
	v_sub_f32_e32 v73, 1.0, v72
	v_add_f32_e32 v72, 1.0, v72
	v_rcp_f32_e32 v72, v72
	s_or_b64 vcc, s[0:1], s[44:45]
	v_mul_f32_e32 v72, v73, v72
	v_mul_f32_e32 v73, 0xbfb8aa3b, v39
	v_exp_f32_e32 v73, v73
	v_cndmask_b32_e64 v72, v72, -v72, s[2:3]
	v_cmp_gt_i32_e64 s[44:45], 64, v12
	v_and_b32_e32 v74, 0x7fffff80, v12
	v_add_f32_e32 v73, 1.0, v73
	v_rcp_f32_e32 v73, v73
	v_cmp_eq_u32_e64 s[6:7], s9, v74
	v_mul_u32_u24_e32 v75, 0x250, v21
	v_lshl_add_u32 v75, v12, 1, v75
	v_cndmask_b32_e64 v39, v39, v73, s[6:7]
	v_cndmask_b32_e64 v39, v39, v72, s[44:45]
	v_cvt_pk_bf16_f32 v39, v39, s0
	v_cndmask_b32_e32 v39, 0, v39, vcc
	ds_write_b16 v75, v39
	v_add3_u32 v66, s14, v22, -3
	v_and_b32_e32 v67, 0x7ff, v66
	v_cmp_ne_u32_e64 s[2:3], 0, v67
	v_lshlrev_b32_e32 v40, 16, v40
	v_lshlrev_b32_e32 v53, 16, v53
	v_cmp_gt_i32_e64 s[44:45], s8, v13
	v_cndmask_b32_e64 v53, 0, v53, s[2:3]
	v_sub_f32_e32 v53, v53, v40
	v_fmac_f32_e32 v40, v31, v53
	v_mul_f32_e64 v72, |v40|, -2.0
	v_mul_f32_e32 v72, 0x3fb8aa3b, v72
	v_exp_f32_e32 v72, v72
	v_cmp_gt_f32_e64 s[2:3], 0, v40
	v_sub_f32_e32 v73, 1.0, v72
	v_add_f32_e32 v72, 1.0, v72
	v_rcp_f32_e32 v72, v72
	s_or_b64 vcc, s[0:1], s[44:45]
	v_mul_f32_e32 v72, v73, v72
	v_mul_f32_e32 v73, 0xbfb8aa3b, v40
	v_exp_f32_e32 v73, v73
	v_cndmask_b32_e64 v72, v72, -v72, s[2:3]
	v_cmp_gt_i32_e64 s[44:45], 64, v13
	v_and_b32_e32 v74, 0x7fffff80, v13
	v_add_f32_e32 v73, 1.0, v73
	v_rcp_f32_e32 v73, v73
	v_cmp_eq_u32_e64 s[6:7], s9, v74
	v_mul_u32_u24_e32 v75, 0x250, v22
	v_lshl_add_u32 v75, v13, 1, v75
	v_cndmask_b32_e64 v40, v40, v73, s[6:7]
	v_cndmask_b32_e64 v40, v40, v72, s[44:45]
	v_cvt_pk_bf16_f32 v40, v40, s0
	v_cndmask_b32_e32 v40, 0, v40, vcc
	ds_write_b16 v75, v40
	v_add3_u32 v66, s14, v23, -3
	v_and_b32_e32 v67, 0x7ff, v66
	v_cmp_ne_u32_e64 s[2:3], 0, v67
	v_lshlrev_b32_e32 v41, 16, v41
	v_lshlrev_b32_e32 v54, 16, v54
	v_cmp_gt_i32_e64 s[44:45], s8, v14
	v_cndmask_b32_e64 v54, 0, v54, s[2:3]
	v_sub_f32_e32 v54, v54, v41
	v_fmac_f32_e32 v41, v32, v54
	v_mul_f32_e64 v72, |v41|, -2.0
	v_mul_f32_e32 v72, 0x3fb8aa3b, v72
	v_exp_f32_e32 v72, v72
	v_cmp_gt_f32_e64 s[2:3], 0, v41
	v_sub_f32_e32 v73, 1.0, v72
	v_add_f32_e32 v72, 1.0, v72
	v_rcp_f32_e32 v72, v72
; __device__ __forceinline__ unsigned f2bf(float f) { return pk2(f, f) & 0xffffu; }
; __device__ __forceinline__ float sigmoidf_(float x) { return __builtin_amdgcn_rcpf(1.0f + __expf(-x)); }
; __device__ __forceinline__ float tanhf_(float x) { const float e = __expf(-2.0f * fabsf(x)); const float t = (1.0f - e) * __builtin_amdgcn_rcpf(1.0f + e); return x < 0.f ? -t : t; }
; __device__ __forceinline__ void rwkv_prep_unit(const Args& c, int u, int l, LAS unsigned char* lds) {
;     ...
;         const bool hp = (tok & (T - 1)) != 0;
;         const float cur = bf2f(P[(size_t)tok * PW + col]);
;         const float pv = bf2f(P[(size_t)(hp ? tok - 1 : tok) * PW + col]);
;         const float prev = hp ? pv : 0.f;
;         float x = cur + (prev - cur) * m_;
;         const float xt = tanhf_(x), xs_ = sigmoidf_(x);
;         x = (j < 64) ? xt : ((j >= 128 && j < 256) ? xs_ : x);
;         xs[t * 296 + j] = (bf16)f2bf(use ? x : 0.f);
	s_or_b64 vcc, s[0:1], s[44:45]
	v_mul_f32_e32 v72, v73, v72
	v_mul_f32_e32 v73, 0xbfb8aa3b, v41
	v_exp_f32_e32 v73, v73
	v_cndmask_b32_e64 v72, v72, -v72, s[2:3]
	v_cmp_gt_i32_e64 s[44:45], 64, v14
	v_and_b32_e32 v74, 0x7fffff80, v14
	v_add_f32_e32 v73, 1.0, v73
	v_rcp_f32_e32 v73, v73
	v_cmp_eq_u32_e64 s[6:7], s9, v74
	v_mul_u32_u24_e32 v75, 0x250, v23
	v_lshl_add_u32 v75, v14, 1, v75
	v_cndmask_b32_e64 v41, v41, v73, s[6:7]
	v_cndmask_b32_e64 v41, v41, v72, s[44:45]
	v_cvt_pk_bf16_f32 v41, v41, s0
	v_cndmask_b32_e32 v41, 0, v41, vcc
	ds_write_b16 v75, v41
	v_add3_u32 v66, s14, v24, -3
	v_and_b32_e32 v67, 0x7ff, v66
	v_cmp_ne_u32_e64 s[2:3], 0, v67
	v_lshlrev_b32_e32 v42, 16, v42
	v_lshlrev_b32_e32 v55, 16, v55
	v_cmp_gt_i32_e64 s[44:45], s8, v15
	v_cndmask_b32_e64 v55, 0, v55, s[2:3]
	v_sub_f32_e32 v55, v55, v42
	v_fmac_f32_e32 v42, v33, v55
	v_mul_f32_e64 v72, |v42|, -2.0
	v_mul_f32_e32 v72, 0x3fb8aa3b, v72
	v_exp_f32_e32 v72, v72
	v_cmp_gt_f32_e64 s[2:3], 0, v42
	v_sub_f32_e32 v73, 1.0, v72
	v_add_f32_e32 v72, 1.0, v72
	v_rcp_f32_e32 v72, v72
	s_or_b64 vcc, s[0:1], s[44:45]
	v_mul_f32_e32 v72, v73, v72
	v_mul_f32_e32 v73, 0xbfb8aa3b, v42
	v_exp_f32_e32 v73, v73
	v_cndmask_b32_e64 v72, v72, -v72, s[2:3]
	v_cmp_gt_i32_e64 s[44:45], 64, v15
	v_and_b32_e32 v74, 0x7fffff80, v15
	v_add_f32_e32 v73, 1.0, v73
	v_rcp_f32_e32 v73, v73
	v_cmp_eq_u32_e64 s[6:7], s9, v74
	v_mul_u32_u24_e32 v75, 0x250, v24
	v_lshl_add_u32 v75, v15, 1, v75
	v_cndmask_b32_e64 v42, v42, v73, s[6:7]
	v_cndmask_b32_e64 v42, v42, v72, s[44:45]
	v_cvt_pk_bf16_f32 v42, v42, s0
	v_cndmask_b32_e32 v42, 0, v42, vcc
	ds_write_b16 v75, v42
	v_add3_u32 v66, s14, v25, -3
	v_and_b32_e32 v67, 0x7ff, v66
	v_cmp_ne_u32_e64 s[2:3], 0, v67
	v_lshlrev_b32_e32 v43, 16, v43
	v_lshlrev_b32_e32 v58, 16, v58
	v_cmp_gt_i32_e64 s[44:45], s8, v16
	v_cndmask_b32_e64 v58, 0, v58, s[2:3]
	v_sub_f32_e32 v58, v58, v43
	v_fmac_f32_e32 v43, v34, v58
	v_mul_f32_e64 v72, |v43|, -2.0
	v_mul_f32_e32 v72, 0x3fb8aa3b, v72
	v_exp_f32_e32 v72, v72
	v_cmp_gt_f32_e64 s[2:3], 0, v43
	v_sub_f32_e32 v73, 1.0, v72
	v_add_f32_e32 v72, 1.0, v72
	v_rcp_f32_e32 v72, v72
	s_or_b64 vcc, s[0:1], s[44:45]
	v_mul_f32_e32 v72, v73, v72
	v_mul_f32_e32 v73, 0xbfb8aa3b, v43
	v_exp_f32_e32 v73, v73
	v_cndmask_b32_e64 v72, v72, -v72, s[2:3]
	v_cmp_gt_i32_e64 s[44:45], 64, v16
	v_and_b32_e32 v74, 0x7fffff80, v16
	v_add_f32_e32 v73, 1.0, v73
	v_rcp_f32_e32 v73, v73
	v_cmp_eq_u32_e64 s[6:7], s9, v74
	v_mul_u32_u24_e32 v75, 0x250, v25
	v_lshl_add_u32 v75, v16, 1, v75
	v_cndmask_b32_e64 v43, v43, v73, s[6:7]
	v_cndmask_b32_e64 v43, v43, v72, s[44:45]
	v_cvt_pk_bf16_f32 v43, v43, s0
	v_cndmask_b32_e32 v43, 0, v43, vcc
	ds_write_b16 v75, v43
	v_add3_u32 v66, s14, v26, -3
	v_and_b32_e32 v67, 0x7ff, v66
	v_cmp_ne_u32_e64 s[2:3], 0, v67
	v_lshlrev_b32_e32 v44, 16, v44
	v_lshlrev_b32_e32 v59, 16, v59
	v_cmp_gt_i32_e64 s[44:45], s8, v17
	v_cndmask_b32_e64 v59, 0, v59, s[2:3]
	v_sub_f32_e32 v59, v59, v44
	v_fmac_f32_e32 v44, v35, v59
	v_mul_f32_e64 v72, |v44|, -2.0
	v_mul_f32_e32 v72, 0x3fb8aa3b, v72
	v_exp_f32_e32 v72, v72
	v_cmp_gt_f32_e64 s[2:3], 0, v44
	v_sub_f32_e32 v73, 1.0, v72
	v_add_f32_e32 v72, 1.0, v72
	v_rcp_f32_e32 v72, v72
	s_or_b64 vcc, s[0:1], s[44:45]
	v_mul_f32_e32 v72, v73, v72
	v_mul_f32_e32 v73, 0xbfb8aa3b, v44
	v_exp_f32_e32 v73, v73
	v_cndmask_b32_e64 v72, v72, -v72, s[2:3]
	v_cmp_gt_i32_e64 s[44:45], 64, v17
	v_and_b32_e32 v74, 0x7fffff80, v17
	v_add_f32_e32 v73, 1.0, v73
	v_rcp_f32_e32 v73, v73
	v_cmp_eq_u32_e64 s[6:7], s9, v74
	v_mul_u32_u24_e32 v75, 0x250, v26
	v_lshl_add_u32 v75, v17, 1, v75
	v_cndmask_b32_e64 v44, v44, v73, s[6:7]
	v_cndmask_b32_e64 v44, v44, v72, s[44:45]
	v_cvt_pk_bf16_f32 v44, v44, s0
	v_cndmask_b32_e32 v44, 0, v44, vcc
	ds_write_b16 v75, v44
	v_add3_u32 v66, s14, v27, -3
	v_and_b32_e32 v67, 0x7ff, v66
	v_cmp_ne_u32_e64 s[2:3], 0, v67
	v_lshlrev_b32_e32 v45, 16, v45
	v_lshlrev_b32_e32 v60, 16, v60
	v_cmp_gt_i32_e64 s[44:45], s8, v18
	v_cndmask_b32_e64 v60, 0, v60, s[2:3]
	v_sub_f32_e32 v60, v60, v45
	v_fmac_f32_e32 v45, v36, v60
	v_mul_f32_e64 v72, |v45|, -2.0
	v_mul_f32_e32 v72, 0x3fb8aa3b, v72
	v_exp_f32_e32 v72, v72
	v_cmp_gt_f32_e64 s[2:3], 0, v45
	v_sub_f32_e32 v73, 1.0, v72
	v_add_f32_e32 v72, 1.0, v72
	v_rcp_f32_e32 v72, v72
	s_or_b64 vcc, s[0:1], s[44:45]
	v_mul_f32_e32 v72, v73, v72
	v_mul_f32_e32 v73, 0xbfb8aa3b, v45
	v_exp_f32_e32 v73, v73
	v_cndmask_b32_e64 v72, v72, -v72, s[2:3]
	v_cmp_gt_i32_e64 s[44:45], 64, v18
	v_and_b32_e32 v74, 0x7fffff80, v18
	v_add_f32_e32 v73, 1.0, v73
	v_rcp_f32_e32 v73, v73
	v_cmp_eq_u32_e64 s[6:7], s9, v74
	v_mul_u32_u24_e32 v75, 0x250, v27
	v_lshl_add_u32 v75, v18, 1, v75
	v_cndmask_b32_e64 v45, v45, v73, s[6:7]
	v_cndmask_b32_e64 v45, v45, v72, s[44:45]
	v_cvt_pk_bf16_f32 v45, v45, s0
	v_cndmask_b32_e32 v45, 0, v45, vcc
	ds_write_b16 v75, v45
	v_add3_u32 v66, s14, v28, -3
	v_and_b32_e32 v67, 0x7ff, v66
	v_cmp_ne_u32_e64 s[2:3], 0, v67
	v_lshlrev_b32_e32 v46, 16, v46
	v_lshlrev_b32_e32 v61, 16, v61
	v_cmp_gt_i32_e64 s[44:45], s8, v19
	v_cndmask_b32_e64 v61, 0, v61, s[2:3]
	v_sub_f32_e32 v61, v61, v46
	v_fmac_f32_e32 v46, v37, v61
	v_mul_f32_e64 v72, |v46|, -2.0
	v_mul_f32_e32 v72, 0x3fb8aa3b, v72
	v_exp_f32_e32 v72, v72
	v_cmp_gt_f32_e64 s[2:3], 0, v46
	v_sub_f32_e32 v73, 1.0, v72
	v_add_f32_e32 v72, 1.0, v72
	v_rcp_f32_e32 v72, v72
	s_or_b64 vcc, s[0:1], s[44:45]
	v_mul_f32_e32 v72, v73, v72
	v_mul_f32_e32 v73, 0xbfb8aa3b, v46
	v_exp_f32_e32 v73, v73
	v_cndmask_b32_e64 v72, v72, -v72, s[2:3]
	v_cmp_gt_i32_e64 s[44:45], 64, v19
	v_and_b32_e32 v74, 0x7fffff80, v19
	v_add_f32_e32 v73, 1.0, v73
	v_rcp_f32_e32 v73, v73
	v_cmp_eq_u32_e64 s[6:7], s9, v74
; #define LAS __attribute__((address_space(3)))
; #define MFMA16(a, b, c) __builtin_amdgcn_mfma_f32_16x16x32_bf16(a, b, c, 0, 0, 0)
; __device__ __forceinline__ unsigned f2bf(float f) { return pk2(f, f) & 0xffffu; }
; __device__ __forceinline__ float sigmoidf_(float x) { return __builtin_amdgcn_rcpf(1.0f + __expf(-x)); }
; __device__ __forceinline__ float tanhf_(float x) { const float e = __expf(-2.0f * fabsf(x)); const float t = (1.0f - e) * __builtin_amdgcn_rcpf(1.0f + e); return x < 0.f ? -t : t; }
; __device__ __forceinline__ void rwkv_prep_unit(const Args& c, int u, int l, LAS unsigned char* lds) {
;     ...
;     for (int it = 0; it < 9; ++it) {
;         const int idx = tid + it * NTHR;
;         const int t = idx / 288, j = idx % 288, tok = tok0 + t;
;         const bool use = (j < 256) || (l > 0);
;         const int col = (j < 256) ? 1536 + j : 1792 + (j - 256);
;         const float m_ = (j < 256) ? mu[1536 + j] : ((l > 0) ? c.in[5 + z_][(size_t)(l - 1) * 32 + (j - 256)] : 0.f);
;         const bool hp = (tok & (T - 1)) != 0;
;         const float cur = bf2f(P[(size_t)tok * PW + col]);
;         const float pv = bf2f(P[(size_t)(hp ? tok - 1 : tok) * PW + col]);
;         const float prev = hp ? pv : 0.f;
;         float x = cur + (prev - cur) * m_;
;         const float xt = tanhf_(x), xs_ = sigmoidf_(x);
;         x = (j < 64) ? xt : ((j >= 128 && j < 256) ? xs_ : x);
;         xs[t * 296 + j] = (bf16)f2bf(use ? x : 0.f);
;     }
;     __syncthreads();
;     f32x4 aw[4], aa[4], ag[4], av[4];
; #pragma unroll
;     for (int jb = 0; jb < 4; ++jb) { aw[jb] = (f32x4){0.f, 0.f, 0.f, 0.f}; aa[jb] = aw[jb]; ag[jb] = aw[jb]; av[jb] = aw[jb]; }
;     const bf16* Lt = ((bf16*)(wsl + WS_LORA)) + (size_t)(64 * w + r) * 288 + q4 * 8;
; #pragma unroll
;     for (int ks = 0; ks < 9; ++ks) {
;         const bf16x8 af = *(const LAS bf16x8*)(xs + r * 296 + ks * 32 + q4 * 8);
; #pragma unroll
;         for (int jb = 0; jb < 4; ++jb) {
;             const bf16x8 bf = *(const bf16x8*)(Lt + (size_t)jb * 16 * 288 + ks * 32);
;             if (ks < 2) aw[jb] = MFMA16(af, bf, aw[jb]); else if (ks < 4) aa[jb] = MFMA16(af, bf, aa[jb]); else if (ks < 8) ag[jb] = MFMA16(af, bf, ag[jb]); else av[jb] = MFMA16(af, bf, av[jb]);
;         }
	v_mul_u32_u24_e32 v75, 0x250, v28
	v_lshl_add_u32 v75, v19, 1, v75
	v_cndmask_b32_e64 v46, v46, v73, s[6:7]
	v_cndmask_b32_e64 v46, v46, v72, s[44:45]
	v_cvt_pk_bf16_f32 v46, v46, s0
	v_cndmask_b32_e32 v46, 0, v46, vcc
	ds_write_b16 v75, v46
	v_add3_u32 v66, s14, v29, -3
	v_and_b32_e32 v67, 0x7ff, v66
	v_cmp_ne_u32_e64 s[2:3], 0, v67
	v_lshlrev_b32_e32 v47, 16, v47
	v_lshlrev_b32_e32 v62, 16, v62
	v_cmp_gt_i32_e64 s[44:45], s8, v20
	v_cndmask_b32_e64 v62, 0, v62, s[2:3]
	v_sub_f32_e32 v62, v62, v47
	v_fmac_f32_e32 v47, v38, v62
	v_mul_f32_e64 v72, |v47|, -2.0
	v_mul_f32_e32 v72, 0x3fb8aa3b, v72
	v_exp_f32_e32 v72, v72
	v_cmp_gt_f32_e64 s[2:3], 0, v47
	v_sub_f32_e32 v73, 1.0, v72
	v_add_f32_e32 v72, 1.0, v72
	v_rcp_f32_e32 v72, v72
	s_or_b64 vcc, s[0:1], s[44:45]
	v_mul_f32_e32 v72, v73, v72
	v_mul_f32_e32 v73, 0xbfb8aa3b, v47
	v_exp_f32_e32 v73, v73
	v_cndmask_b32_e64 v72, v72, -v72, s[2:3]
	v_cmp_gt_i32_e64 s[44:45], 64, v20
	v_and_b32_e32 v74, 0x7fffff80, v20
	v_add_f32_e32 v73, 1.0, v73
	v_rcp_f32_e32 v73, v73
	v_cmp_eq_u32_e64 s[6:7], s9, v74
	v_mul_u32_u24_e32 v75, 0x250, v29
	v_lshl_add_u32 v75, v20, 1, v75
	v_cndmask_b32_e64 v47, v47, v73, s[6:7]
	v_cndmask_b32_e64 v47, v47, v72, s[44:45]
	v_cvt_pk_bf16_f32 v47, v47, s0
	v_cndmask_b32_e32 v47, 0, v47, vcc
	ds_write_b16 v75, v47
	v_mov_b32_e32 v103, 0
	v_and_b32_e32 v117, 15, v116
	v_mul_u32_u24_e32 v4, 0x250, v117
	s_and_b32 s0, s16, 0xffffffc0
	v_or_b32_e32 v68, s0, v117
	v_mov_b64_e32 v[2:3], s[24:25]
	s_movk_i32 s0, 0x240
	v_mad_i64_i32 v[2:3], s[0:1], v68, s0, v[2:3]
	v_and_b32_e32 v0, 48, v116
	v_lshl_add_u64 v[2:3], v[2:3], 0, v[0:1]
	s_mov_b64 s[0:1], 0x6700000
	v_lshl_add_u64 v[48:49], v[2:3], 0, s[0:1]
	s_mov_b32 s0, 0x6700000
	v_add_co_u32_e32 v8, vcc, s0, v2
	s_mov_b32 s0, 0x6702000
	s_nop 0
	v_addc_co_u32_e32 v9, vcc, 0, v3, vcc
	v_add_co_u32_e32 v56, vcc, s0, v2
	s_mov_b32 s0, 0x6704000
	s_nop 0
	v_addc_co_u32_e32 v57, vcc, 0, v3, vcc
	v_add_co_u32_e32 v50, vcc, s0, v2
	s_waitcnt lgkmcnt(0)
	s_nop 0
	v_addc_co_u32_e32 v51, vcc, 0, v3, vcc
	s_barrier
	v_add3_u32 v0, 0, v4, v0
	v_ashrrev_i32_e32 v69, 31, v68
	s_mov_b64 s[0:1], 0x6700000
	v_lshl_add_u64 v[86:87], v[2:3], 0, s[0:1]
	s_mov_b64 s[0:1], 0x6702000
	v_lshl_add_u64 v[88:89], v[2:3], 0, s[0:1]
	s_mov_b64 s[0:1], 0x6704000
	v_lshl_add_u64 v[90:91], v[2:3], 0, s[0:1]
	s_mov_b64 s[0:1], 0x6706000
	v_lshl_add_u64 v[188:189], v[2:3], 0, s[0:1]
	ds_read_b128 v[204:207], v0
	ds_read_b128 v[208:211], v0 offset:64
	ds_read_b128 v[212:215], v0 offset:128
	ds_read_b128 v[216:219], v0 offset:192
	ds_read_b128 v[220:223], v0 offset:256
	ds_read_b128 v[224:227], v0 offset:320
	ds_read_b128 v[228:231], v0 offset:384
	ds_read_b128 v[232:235], v0 offset:448
	ds_read_b128 v[236:239], v0 offset:512
	global_load_dwordx4 v[240:243], v[86:87], off
	global_load_dwordx4 v[94:97], v[88:89], off offset:1024
	global_load_dwordx4 v[98:101], v[90:91], off offset:2048
	global_load_dwordx4 v[104:107], v[188:189], off offset:3072
	global_load_dwordx4 v[108:111], v[86:87], off offset:64
	global_load_dwordx4 v[112:115], v[88:89], off offset:1088
	global_load_dwordx4 v[136:139], v[90:91], off offset:2112
	global_load_dwordx4 v[140:143], v[188:189], off offset:3136
	global_load_dwordx4 v[144:147], v[86:87], off offset:128
	global_load_dwordx4 v[148:151], v[88:89], off offset:1152
	global_load_dwordx4 v[152:155], v[90:91], off offset:2176
	global_load_dwordx4 v[156:159], v[188:189], off offset:3200
	global_load_dwordx4 v[160:163], v[86:87], off offset:192
	global_load_dwordx4 v[164:167], v[88:89], off offset:1216
	global_load_dwordx4 v[168:171], v[90:91], off offset:2240
	global_load_dwordx4 v[172:175], v[188:189], off offset:3264
	global_load_dwordx4 v[184:187], v[86:87], off offset:256
	global_load_dwordx4 v[70:73], v[88:89], off offset:1280
	v_lshl_add_u64 v[74:75], v[68:69], 2, s[40:41]
	s_waitcnt vmcnt(17) lgkmcnt(8)
	v_mfma_f32_16x16x32_bf16 v[16:19], v[204:207], v[240:243], 0
	global_load_dwordx4 v[240:243], v[90:91], off offset:2304
	s_waitcnt vmcnt(17)
	v_mfma_f32_16x16x32_bf16 v[12:15], v[204:207], v[94:97], 0
	global_load_dwordx4 v[94:97], v[188:189], off offset:3328
	s_waitcnt vmcnt(17)
	v_mfma_f32_16x16x32_bf16 v[8:11], v[204:207], v[98:101], 0
	global_load_dwordx4 v[98:101], v[86:87], off offset:320
	s_waitcnt vmcnt(17)
	v_mfma_f32_16x16x32_bf16 v[4:7], v[204:207], v[104:107], 0
	global_load_dwordx4 v[104:107], v[88:89], off offset:1344
	s_waitcnt vmcnt(17) lgkmcnt(7)
	v_mfma_f32_16x16x32_bf16 v[16:19], v[208:211], v[108:111], v[16:19]
	global_load_dwordx4 v[108:111], v[90:91], off offset:2368
	s_waitcnt vmcnt(17)
	v_mfma_f32_16x16x32_bf16 v[12:15], v[208:211], v[112:115], v[12:15]
	global_load_dwordx4 v[112:115], v[188:189], off offset:3392
	s_waitcnt vmcnt(17)
; #define LAS __attribute__((address_space(3)))
; #define MFMA16(a, b, c) __builtin_amdgcn_mfma_f32_16x16x32_bf16(a, b, c, 0, 0, 0)
; __device__ __forceinline__ void rwkv_prep_unit(const Args& c, int u, int l, LAS unsigned char* lds) {
;     ...
;     for (int ks = 0; ks < 9; ++ks) {
;         const bf16x8 af = *(const LAS bf16x8*)(xs + r * 296 + ks * 32 + q4 * 8);
; #pragma unroll
;         for (int jb = 0; jb < 4; ++jb) {
;             const bf16x8 bf = *(const bf16x8*)(Lt + (size_t)jb * 16 * 288 + ks * 32);
;             if (ks < 2) aw[jb] = MFMA16(af, bf, aw[jb]); else if (ks < 4) aa[jb] = MFMA16(af, bf, aa[jb]); else if (ks < 8) ag[jb] = MFMA16(af, bf, ag[jb]); else av[jb] = MFMA16(af, bf, av[jb]);
;         }
;     }
;     float rr[4][4], k2[4][4], vv[4][4], dec[4][4], asg[4][4], kkr[4][4], rkv[4];
; #pragma unroll
;     for (int jb = 0; jb < 4; ++jb) {
;         const int ch = 64 * w + 16 * jb + r;
;         const float mu_r = mu[ch], mu_k = mu[512 + ch], mu_v = mu[1024 + ch];
;         const float w0 = c.in[6 + z_][l * 512 + ch], a0 = c.in[8 + z_][l * 512 + ch], kk_ = c.in[13 + z_][l * 512 + ch], ka_ = c.in[14 + z_][l * 512 + ch];
;         rkv[jb] = c.in[15 + z_][l * 512 + ch];
;         const float v0 = (l > 0) ? c.in[11 + z_][(l - 1) * 512 + ch] : 0.f;
	v_mfma_f32_16x16x32_bf16 v[8:11], v[208:211], v[136:139], v[8:11]
	global_load_dwordx4 v[136:139], v[86:87], off offset:384
	s_waitcnt vmcnt(17)
	v_mfma_f32_16x16x32_bf16 v[4:7], v[208:211], v[140:143], v[4:7]
	global_load_dwordx4 v[140:143], v[88:89], off offset:1408
	s_waitcnt vmcnt(17) lgkmcnt(6)
	v_mfma_f32_16x16x32_bf16 v[20:23], v[212:215], v[144:147], 0
	global_load_dwordx4 v[144:147], v[90:91], off offset:2432
	s_waitcnt vmcnt(17)
	v_mfma_f32_16x16x32_bf16 v[24:27], v[212:215], v[148:151], 0
	global_load_dwordx4 v[148:151], v[188:189], off offset:3456
	s_waitcnt vmcnt(17)
	v_mfma_f32_16x16x32_bf16 v[28:31], v[212:215], v[152:155], 0
	global_load_dwordx4 v[152:155], v[86:87], off offset:448
	s_waitcnt vmcnt(17)
	v_mfma_f32_16x16x32_bf16 v[32:35], v[212:215], v[156:159], 0
	global_load_dwordx4 v[156:159], v[88:89], off offset:1472
	s_waitcnt vmcnt(17) lgkmcnt(5)
	v_mfma_f32_16x16x32_bf16 v[20:23], v[216:219], v[160:163], v[20:23]
	global_load_dwordx4 v[160:163], v[90:91], off offset:2496
	s_waitcnt vmcnt(17)
	v_mfma_f32_16x16x32_bf16 v[24:27], v[216:219], v[164:167], v[24:27]
	global_load_dwordx4 v[164:167], v[188:189], off offset:3520
	s_waitcnt vmcnt(17)
	v_mfma_f32_16x16x32_bf16 v[28:31], v[216:219], v[168:171], v[28:31]
	global_load_dwordx4 v[168:171], v[86:87], off offset:512
	s_waitcnt vmcnt(17)
	v_mfma_f32_16x16x32_bf16 v[32:35], v[216:219], v[172:175], v[32:35]
	global_load_dwordx4 v[172:175], v[88:89], off offset:1536
	s_waitcnt vmcnt(17) lgkmcnt(4)
	v_mfma_f32_16x16x32_bf16 v[60:63], v[220:223], v[184:187], 0
	global_load_dwordx4 v[184:187], v[90:91], off offset:2560
	s_waitcnt vmcnt(17)
	v_mfma_f32_16x16x32_bf16 v[52:55], v[220:223], v[70:73], 0
	global_load_dwordx4 v[70:73], v[188:189], off offset:3584
	s_waitcnt vmcnt(17)
	v_mfma_f32_16x16x32_bf16 v[44:47], v[220:223], v[240:243], 0
	s_waitcnt vmcnt(16)
	v_mfma_f32_16x16x32_bf16 v[36:39], v[220:223], v[94:97], 0
	s_waitcnt vmcnt(15) lgkmcnt(3)
	v_mfma_f32_16x16x32_bf16 v[60:63], v[224:227], v[98:101], v[60:63]
	s_waitcnt vmcnt(14)
	v_mfma_f32_16x16x32_bf16 v[52:55], v[224:227], v[104:107], v[52:55]
	s_waitcnt vmcnt(13)
	v_mfma_f32_16x16x32_bf16 v[44:47], v[224:227], v[108:111], v[44:47]
	s_waitcnt vmcnt(12)
	v_mfma_f32_16x16x32_bf16 v[36:39], v[224:227], v[112:115], v[36:39]
	s_waitcnt vmcnt(11) lgkmcnt(2)
	v_mfma_f32_16x16x32_bf16 v[60:63], v[228:231], v[136:139], v[60:63]
	s_waitcnt vmcnt(10)
	v_mfma_f32_16x16x32_bf16 v[52:55], v[228:231], v[140:143], v[52:55]
	s_waitcnt vmcnt(9)
	v_mfma_f32_16x16x32_bf16 v[44:47], v[228:231], v[144:147], v[44:47]
	s_waitcnt vmcnt(8)
	v_mfma_f32_16x16x32_bf16 v[36:39], v[228:231], v[148:151], v[36:39]
	s_waitcnt vmcnt(7) lgkmcnt(1)
	v_mfma_f32_16x16x32_bf16 v[60:63], v[232:235], v[152:155], v[60:63]
	s_waitcnt vmcnt(6)
	v_mfma_f32_16x16x32_bf16 v[52:55], v[232:235], v[156:159], v[52:55]
	s_waitcnt vmcnt(5)
	v_mfma_f32_16x16x32_bf16 v[44:47], v[232:235], v[160:163], v[44:47]
	s_waitcnt vmcnt(4)
	v_mfma_f32_16x16x32_bf16 v[36:39], v[232:235], v[164:167], v[36:39]
	s_waitcnt vmcnt(3) lgkmcnt(0)
	v_mfma_f32_16x16x32_bf16 v[64:67], v[236:239], v[168:171], 0
	s_waitcnt vmcnt(2)
	v_mfma_f32_16x16x32_bf16 v[56:59], v[236:239], v[172:175], 0
	s_waitcnt vmcnt(1)
	v_mfma_f32_16x16x32_bf16 v[48:51], v[236:239], v[184:187], 0
	s_waitcnt vmcnt(0)
	v_mfma_f32_16x16x32_bf16 v[40:43], v[236:239], v[70:73], 0
	s_movk_i32 s0, 0x1000
	s_load_dwordx2 s[2:3], s[12:13], 0x78
	s_load_dwordx2 s[6:7], s[12:13], 0x30
	s_load_dwordx2 s[4:5], s[12:13], 0x40
	s_load_dwordx4 s[8:11], s[12:13], 0x68
	v_add_co_u32_e32 v2, vcc, s0, v74
	v_readlane_b32 s0, v250, 50
	s_nop 0
	v_addc_co_u32_e32 v3, vcc, 0, v75, vcc
	global_load_dword v129, v[74:75], off
	global_load_dword v130, v[74:75], off offset:2048
	global_load_dword v102, v[2:3], off
	v_add_u32_e32 v2, s0, v68
	v_ashrrev_i32_e32 v3, 31, v2
	v_lshlrev_b64 v[2:3], 2, v[2:3]
	s_waitcnt lgkmcnt(0)
	v_lshl_add_u64 v[76:77], s[6:7], 0, v[2:3]
	v_lshl_add_u64 v[78:79], s[4:5], 0, v[2:3]
	v_lshl_add_u64 v[80:81], s[8:9], 0, v[2:3]
	v_lshl_add_u64 v[82:83], s[10:11], 0, v[2:3]
	v_lshl_add_u64 v[84:85], s[2:3], 0, v[2:3]
	global_load_dword v131, v[76:77], off
	global_load_dword v133, v[78:79], off
	global_load_dword v132, v[80:81], off
	global_load_dword v135, v[82:83], off
	global_load_dword v134, v[84:85], off
	s_and_b64 vcc, exec, s[42:43]
	s_cbranch_vccnz .LBB0_355
	s_load_dwordx2 s[0:1], s[12:13], 0x58
	v_readlane_b32 s2, v247, 25
	v_readlane_b32 s3, v247, 26
	s_nop 0
	v_add_u32_e32 v2, s2, v68
	v_ashrrev_i32_e32 v3, 31, v2
	s_waitcnt lgkmcnt(0)
	v_lshl_add_u64 v[2:3], v[2:3], 2, s[0:1]
	global_load_dword v103, v[2:3], off
